# plus: residual epilogues of out/down projections rewritten (gate loaded once per unit, x loads 6 pieces ahead instead of 32 serial round trips), K-split slab combines (phase 7 sample rows, final phase
# speedup vs baseline: 1.0579x; 1.0434x over previous
.LBB0_16:
	v_ashrrev_i32_e32 v2, 9, v12
	v_and_b32_e32 v0, 0x7fc, v13
	v_ashrrev_i32_e32 v3, 31, v2
	v_lshlrev_b32_e32 v0, 2, v0
	v_lshl_add_u64 v[4:5], s[96:97], 0, v[0:1]
	v_lshlrev_b64 v[10:11], 13, v[2:3]
	v_lshl_add_u64 v[2:3], v[4:5], 0, v[10:11]
	s_mov_b32 s12, 0x100000
	global_load_dwordx4 v[88:91], v[2:3], off
	v_add_co_u32_e32 v2, vcc, s12, v2
	s_nop 1
	v_addc_co_u32_e32 v3, vcc, 0, v3, vcc
	global_load_dwordx4 v[92:95], v[2:3], off
	v_add_co_u32_e32 v2, vcc, s12, v2
	s_nop 1
	v_addc_co_u32_e32 v3, vcc, 0, v3, vcc
	global_load_dwordx4 v[96:99], v[2:3], off
	v_add_co_u32_e32 v2, vcc, s12, v2
	s_nop 1
	v_addc_co_u32_e32 v3, vcc, 0, v3, vcc
	global_load_dwordx4 v[100:103], v[2:3], off
	v_add_co_u32_e32 v2, vcc, s12, v2
	s_nop 1
	v_addc_co_u32_e32 v3, vcc, 0, v3, vcc
	global_load_dwordx4 v[104:107], v[2:3], off
	v_add_co_u32_e32 v2, vcc, s12, v2
	s_nop 1
	v_addc_co_u32_e32 v3, vcc, 0, v3, vcc
	global_load_dwordx4 v[108:111], v[2:3], off
	v_add_co_u32_e32 v2, vcc, s12, v2
	s_nop 1
	v_addc_co_u32_e32 v3, vcc, 0, v3, vcc
	global_load_dwordx4 v[112:115], v[2:3], off
	v_add_co_u32_e32 v2, vcc, s12, v2
	s_nop 1
	v_addc_co_u32_e32 v3, vcc, 0, v3, vcc
	global_load_dwordx4 v[120:123], v[2:3], off
	v_add_co_u32_e32 v2, vcc, s12, v2
	s_nop 1
	v_addc_co_u32_e32 v3, vcc, 0, v3, vcc
	global_load_dwordx4 v[124:127], v[2:3], off
	v_add_co_u32_e32 v2, vcc, s12, v2
	s_nop 1
	v_addc_co_u32_e32 v3, vcc, 0, v3, vcc
	global_load_dwordx4 v[128:131], v[2:3], off
	v_add_co_u32_e32 v2, vcc, s12, v2
	s_nop 1
	v_addc_co_u32_e32 v3, vcc, 0, v3, vcc
	global_load_dwordx4 v[136:139], v[2:3], off
	v_add_co_u32_e32 v2, vcc, s12, v2
	s_nop 1
	v_addc_co_u32_e32 v3, vcc, 0, v3, vcc
	global_load_dwordx4 v[140:143], v[2:3], off
	v_add_co_u32_e32 v2, vcc, s12, v2
	s_nop 1
	v_addc_co_u32_e32 v3, vcc, 0, v3, vcc
	global_load_dwordx4 v[144:147], v[2:3], off
	v_add_co_u32_e32 v2, vcc, s12, v2
	s_nop 1
	v_addc_co_u32_e32 v3, vcc, 0, v3, vcc
	global_load_dwordx4 v[148:151], v[2:3], off
	v_add_co_u32_e32 v2, vcc, s12, v2
	s_nop 1
	v_addc_co_u32_e32 v3, vcc, 0, v3, vcc
	global_load_dwordx4 v[224:227], v[2:3], off
	v_add_co_u32_e32 v2, vcc, s12, v2
	s_nop 1
	v_addc_co_u32_e32 v3, vcc, 0, v3, vcc
	global_load_dwordx4 v[228:231], v[2:3], off
	v_add_co_u32_e32 v2, vcc, s12, v2
	s_nop 1
	v_addc_co_u32_e32 v3, vcc, 0, v3, vcc
	global_load_dwordx4 v[232:235], v[2:3], off
	v_add_co_u32_e32 v2, vcc, s12, v2
	s_nop 1
	v_addc_co_u32_e32 v3, vcc, 0, v3, vcc
	global_load_dwordx4 v[236:239], v[2:3], off
	v_add_co_u32_e32 v2, vcc, s12, v2
	s_nop 1
	v_addc_co_u32_e32 v3, vcc, 0, v3, vcc
	global_load_dwordx4 v[240:243], v[2:3], off
	v_add_co_u32_e32 v2, vcc, s12, v2
	s_nop 1
	v_addc_co_u32_e32 v3, vcc, 0, v3, vcc
	global_load_dwordx4 v[244:247], v[2:3], off
	v_add_co_u32_e32 v2, vcc, s12, v2
	s_nop 1
	v_addc_co_u32_e32 v3, vcc, 0, v3, vcc
	global_load_dwordx4 v[64:67], v[2:3], off
	v_add_co_u32_e32 v2, vcc, s12, v2
	s_nop 1
	v_addc_co_u32_e32 v3, vcc, 0, v3, vcc
	global_load_dwordx4 v[168:171], v[2:3], off
	v_lshl_add_u64 v[10:11], s[22:23], 0, v[10:11]
	v_lshl_add_u64 v[10:11], v[10:11], 0, v[0:1]
	v_add_u32_e32 v13, s36, v13
	v_ashrrev_i32_e32 v2, 13, v12
	v_add_u32_e32 v2, 4, v2
	v_mul_hi_i32_i24_e32 v3, 0xc000, v2
	v_mul_i32_i24_e32 v2, 0xc000, v2
	v_lshl_add_u64 v[2:3], s[24:25], 0, v[2:3]
	v_lshl_add_u64 v[2:3], v[2:3], 0, v[0:1]
	s_mov_b32 s12, 0x4f0a000
	v_add_co_u32_e32 v2, vcc, s12, v2
	s_brev_b32 s12, 32
	s_nop 0
	v_addc_co_u32_e32 v3, vcc, 0, v3, vcc
	v_add_co_u32_e32 v10, vcc, s12, v10
	s_nop 1
	v_addc_co_u32_e32 v11, vcc, 0, v11, vcc
	global_load_dwordx4 v[2:5], v[2:3], off
	v_add_u32_e32 v12, s18, v12
	global_load_dwordx4 v[14:17], v[10:11], off
	v_cmp_lt_i32_e32 vcc, s41, v12
	s_or_b64 s[38:39], vcc, s[38:39]
	s_waitcnt vmcnt(23)
	v_pk_add_f32 v[8:9], v[88:89], 0 op_sel_hi:[1,0]
	v_pk_add_f32 v[6:7], v[90:91], 0 op_sel_hi:[1,0]
	s_waitcnt vmcnt(22)
	v_pk_add_f32 v[8:9], v[8:9], v[92:93]
	v_pk_add_f32 v[6:7], v[6:7], v[94:95]
	s_waitcnt vmcnt(21)
	v_pk_add_f32 v[8:9], v[8:9], v[96:97]
	v_pk_add_f32 v[6:7], v[6:7], v[98:99]
	s_waitcnt vmcnt(20)
	v_pk_add_f32 v[8:9], v[8:9], v[100:101]
	v_pk_add_f32 v[6:7], v[6:7], v[102:103]
	s_waitcnt vmcnt(19)
	v_pk_add_f32 v[8:9], v[8:9], v[104:105]
	v_pk_add_f32 v[6:7], v[6:7], v[106:107]
	s_waitcnt vmcnt(18)
	v_pk_add_f32 v[8:9], v[8:9], v[108:109]
	v_pk_add_f32 v[6:7], v[6:7], v[110:111]
	s_waitcnt vmcnt(17)
	v_pk_add_f32 v[8:9], v[8:9], v[112:113]
	v_pk_add_f32 v[6:7], v[6:7], v[114:115]
	s_waitcnt vmcnt(16)
	v_pk_add_f32 v[8:9], v[8:9], v[120:121]
	v_pk_add_f32 v[6:7], v[6:7], v[122:123]
	s_waitcnt vmcnt(15)
	v_pk_add_f32 v[8:9], v[8:9], v[124:125]
	v_pk_add_f32 v[6:7], v[6:7], v[126:127]
	s_waitcnt vmcnt(14)
	v_pk_add_f32 v[8:9], v[8:9], v[128:129]
	v_pk_add_f32 v[6:7], v[6:7], v[130:131]
	s_waitcnt vmcnt(13)
	v_pk_add_f32 v[8:9], v[8:9], v[136:137]
	v_pk_add_f32 v[6:7], v[6:7], v[138:139]
	s_waitcnt vmcnt(12)
	v_pk_add_f32 v[8:9], v[8:9], v[140:141]
	v_pk_add_f32 v[6:7], v[6:7], v[142:143]
	s_waitcnt vmcnt(11)
	v_pk_add_f32 v[8:9], v[8:9], v[144:145]
	v_pk_add_f32 v[6:7], v[6:7], v[146:147]
	s_waitcnt vmcnt(10)
	v_pk_add_f32 v[8:9], v[8:9], v[148:149]
	v_pk_add_f32 v[6:7], v[6:7], v[150:151]
	s_waitcnt vmcnt(9)
	v_pk_add_f32 v[8:9], v[8:9], v[224:225]
	v_pk_add_f32 v[6:7], v[6:7], v[226:227]
	s_waitcnt vmcnt(8)
	v_pk_add_f32 v[8:9], v[8:9], v[228:229]
	v_pk_add_f32 v[6:7], v[6:7], v[230:231]
	s_waitcnt vmcnt(7)
	v_pk_add_f32 v[8:9], v[8:9], v[232:233]
	v_pk_add_f32 v[6:7], v[6:7], v[234:235]
	s_waitcnt vmcnt(6)
	v_pk_add_f32 v[8:9], v[8:9], v[236:237]
	v_pk_add_f32 v[6:7], v[6:7], v[238:239]
	s_waitcnt vmcnt(5)
	v_pk_add_f32 v[8:9], v[8:9], v[240:241]
	v_pk_add_f32 v[6:7], v[6:7], v[242:243]
	s_waitcnt vmcnt(4)
	v_pk_add_f32 v[8:9], v[8:9], v[244:245]
	v_pk_add_f32 v[6:7], v[6:7], v[246:247]
	s_waitcnt vmcnt(3)
	v_pk_add_f32 v[8:9], v[8:9], v[64:65]
	v_pk_add_f32 v[6:7], v[6:7], v[66:67]
	s_waitcnt vmcnt(2)
	v_pk_add_f32 v[8:9], v[8:9], v[168:169]
	v_pk_add_f32 v[6:7], v[6:7], v[170:171]
	s_waitcnt vmcnt(0)
	v_pk_fma_f32 v[4:5], v[6:7], v[4:5], v[16:17]
	v_pk_fma_f32 v[2:3], v[8:9], v[2:3], v[14:15]
	global_store_dwordx4 v[10:11], v[2:5], off
	s_andn2_b64 exec, exec, s[38:39]
	s_cbranch_execnz .LBB0_16

.LBB0_37:
	s_add_i32 s69, s48, 2
	s_add_u32 s46, s0, 0x100
	s_addc_u32 s47, s1, 0
	s_add_i32 s70, 0, 0x10000
	v_add_u32_e32 v156, s70, v153
	ds_read_b128 v[140:143], v156
	ds_read_b128 v[144:147], v156 offset:1024
	ds_read_b128 v[148:151], v156 offset:2048
	ds_read_b128 v[168:171], v156 offset:3072
	s_cmp_eq_u32 s12, s48
	s_cselect_b32 s48, s44, s13
	s_cselect_b32 s51, s43, s47
	s_cselect_b32 s50, s42, s46
	s_cselect_b32 s49, s45, s68
	v_lshl_add_u64 v[156:157], s[0:1], 0, v[136:137]
	s_add_i32 m0, s53, 0xc000
	ds_read_b128 v[172:175], v155
	ds_read_b128 v[176:179], v155 offset:1024
	ds_read_b128 v[180:183], v155 offset:2048
	ds_read_b128 v[184:187], v155 offset:3072
	ds_read_b128 v[188:191], v155 offset:4096
	ds_read_b128 v[192:195], v155 offset:5120
	ds_read_b128 v[196:199], v155 offset:6144
	ds_read_b128 v[224:227], v155 offset:7168
	global_load_lds_dwordx4 v[156:157], off
	v_lshl_add_u64 v[156:157], s[0:1], 0, v[138:139]
	s_add_i32 m0, s53, 0xe000
	s_nop 0
	global_load_lds_dwordx4 v[156:157], off
	s_waitcnt lgkmcnt(8)
	s_barrier
	s_waitcnt lgkmcnt(0)
	s_setprio 1
	s_waitcnt lgkmcnt(0)
	v_mfma_f32_16x16x32_bf16 v[126:129], v[140:143], v[172:175], v[126:129]
	v_mfma_f32_16x16x32_bf16 v[122:125], v[148:151], v[172:175], v[122:125]
	v_mfma_f32_16x16x32_bf16 v[110:113], v[140:143], v[180:183], v[110:113]
	v_mfma_f32_16x16x32_bf16 v[106:109], v[148:151], v[180:183], v[106:109]
	v_mfma_f32_16x16x32_bf16 v[94:97], v[140:143], v[188:191], v[94:97]
	v_mfma_f32_16x16x32_bf16 v[90:93], v[148:151], v[188:191], v[90:93]
	v_mfma_f32_16x16x32_bf16 v[78:81], v[140:143], v[196:199], v[78:81]
	v_mfma_f32_16x16x32_bf16 v[74:77], v[148:151], v[196:199], v[74:77]
	v_mfma_f32_16x16x32_bf16 v[126:129], v[144:147], v[176:179], v[126:129]
	v_mfma_f32_16x16x32_bf16 v[122:125], v[168:171], v[176:179], v[122:125]
	v_mfma_f32_16x16x32_bf16 v[110:113], v[144:147], v[184:187], v[110:113]
	v_mfma_f32_16x16x32_bf16 v[106:109], v[168:171], v[184:187], v[106:109]
	v_mfma_f32_16x16x32_bf16 v[94:97], v[144:147], v[192:195], v[94:97]
	v_mfma_f32_16x16x32_bf16 v[90:93], v[168:171], v[192:195], v[90:93]
	v_mfma_f32_16x16x32_bf16 v[78:81], v[144:147], v[224:227], v[78:81]
	v_mfma_f32_16x16x32_bf16 v[74:77], v[168:171], v[224:227], v[74:77]
	s_setprio 0
	s_barrier
	s_add_i32 s71, 0, 0x14000
	v_add_u32_e32 v156, s71, v153
	s_add_i32 s0, s70, s52
	ds_read_b128 v[228:231], v156
	ds_read_b128 v[232:235], v156 offset:1024
	ds_read_b128 v[236:239], v156 offset:2048
	ds_read_b128 v[240:243], v156 offset:3072
	v_lshl_add_u64 v[156:157], s[48:49], 0, v[0:1]
	s_mov_b32 m0, s0
	v_lshl_add_u64 v[200:201], s[48:49], 0, v[130:131]
	global_load_lds_dwordx4 v[156:157], off
	s_add_i32 m0, s0, 0x2000
	s_nop 0
	global_load_lds_dwordx4 v[200:201], off
	s_barrier
	s_waitcnt lgkmcnt(0)
	s_setprio 1
	s_waitcnt lgkmcnt(0)
	v_mfma_f32_16x16x32_bf16 v[118:121], v[228:231], v[172:175], v[118:121]
	v_mfma_f32_16x16x32_bf16 v[114:117], v[236:239], v[172:175], v[114:117]
	v_mfma_f32_16x16x32_bf16 v[102:105], v[228:231], v[180:183], v[102:105]
	v_mfma_f32_16x16x32_bf16 v[98:101], v[236:239], v[180:183], v[98:101]
	v_mfma_f32_16x16x32_bf16 v[86:89], v[228:231], v[188:191], v[86:89]
	v_mfma_f32_16x16x32_bf16 v[82:85], v[236:239], v[188:191], v[82:85]
	v_mfma_f32_16x16x32_bf16 v[70:73], v[228:231], v[196:199], v[70:73]
	v_mfma_f32_16x16x32_bf16 v[66:69], v[236:239], v[196:199], v[66:69]
	v_mfma_f32_16x16x32_bf16 v[118:121], v[232:235], v[176:179], v[118:121]
	v_mfma_f32_16x16x32_bf16 v[114:117], v[240:243], v[176:179], v[114:117]
	v_mfma_f32_16x16x32_bf16 v[102:105], v[232:235], v[184:187], v[102:105]
	v_mfma_f32_16x16x32_bf16 v[98:101], v[240:243], v[184:187], v[98:101]
	v_mfma_f32_16x16x32_bf16 v[86:89], v[232:235], v[192:195], v[86:89]
	v_mfma_f32_16x16x32_bf16 v[82:85], v[240:243], v[192:195], v[82:85]
	v_mfma_f32_16x16x32_bf16 v[70:73], v[232:235], v[224:227], v[70:73]
	v_mfma_f32_16x16x32_bf16 v[66:69], v[240:243], v[224:227], v[66:69]
	s_setprio 0
	s_mov_b32 m0, s53
	v_lshl_add_u64 v[210:211], s[50:51], 0, v[134:135]
	s_barrier
	ds_read_b128 v[172:175], v155 offset:16384
	ds_read_b128 v[176:179], v155 offset:17408
	ds_read_b128 v[180:183], v155 offset:18432
	ds_read_b128 v[184:187], v155 offset:19456
	ds_read_b128 v[188:191], v155 offset:20480
	ds_read_b128 v[192:195], v155 offset:21504
	ds_read_b128 v[196:199], v155 offset:22528
	ds_read_b128 v[224:227], v155 offset:23552
	global_load_lds_dwordx4 v[210:211], off
	v_lshl_add_u64 v[212:213], s[50:51], 0, v[132:133]
	s_mov_b32 m0, s54
	s_nop 0
	global_load_lds_dwordx4 v[212:213], off
	s_barrier
	s_waitcnt lgkmcnt(0)
	s_setprio 1
	s_waitcnt lgkmcnt(0)
	v_mfma_f32_16x16x32_bf16 v[62:65], v[140:143], v[172:175], v[62:65]
	v_mfma_f32_16x16x32_bf16 v[58:61], v[148:151], v[172:175], v[58:61]
	v_mfma_f32_16x16x32_bf16 v[46:49], v[140:143], v[180:183], v[46:49]
	v_mfma_f32_16x16x32_bf16 v[42:45], v[148:151], v[180:183], v[42:45]
	v_mfma_f32_16x16x32_bf16 v[30:33], v[140:143], v[188:191], v[30:33]
	v_mfma_f32_16x16x32_bf16 v[26:29], v[148:151], v[188:191], v[26:29]
	v_mfma_f32_16x16x32_bf16 v[14:17], v[140:143], v[196:199], v[14:17]
	v_mfma_f32_16x16x32_bf16 v[10:13], v[148:151], v[196:199], v[10:13]
	v_mfma_f32_16x16x32_bf16 v[62:65], v[144:147], v[176:179], v[62:65]
	v_mfma_f32_16x16x32_bf16 v[58:61], v[168:171], v[176:179], v[58:61]
	v_mfma_f32_16x16x32_bf16 v[46:49], v[144:147], v[184:187], v[46:49]
	v_mfma_f32_16x16x32_bf16 v[42:45], v[168:171], v[184:187], v[42:45]
	v_mfma_f32_16x16x32_bf16 v[30:33], v[144:147], v[192:195], v[30:33]
	v_mfma_f32_16x16x32_bf16 v[26:29], v[168:171], v[192:195], v[26:29]
	v_mfma_f32_16x16x32_bf16 v[14:17], v[144:147], v[224:227], v[14:17]
	v_mfma_f32_16x16x32_bf16 v[10:13], v[168:171], v[224:227], v[10:13]
	s_setprio 0
	s_barrier
	s_add_u32 s0, s48, 0x160000
	s_addc_u32 s1, s49, 0
	s_add_i32 s70, s71, s52
	v_lshl_add_u64 v[140:141], s[0:1], 0, v[0:1]
	s_mov_b32 m0, s70
	s_nop 0
	global_load_lds_dwordx4 v[140:141], off
	v_lshl_add_u64 v[140:141], s[0:1], 0, v[130:131]
	s_add_i32 m0, s70, 0x2000
	s_nop 0
	global_load_lds_dwordx4 v[140:141], off
	s_waitcnt vmcnt(6)
	s_barrier
	s_setprio 1
	v_mfma_f32_16x16x32_bf16 v[54:57], v[228:231], v[172:175], v[54:57]
	v_mfma_f32_16x16x32_bf16 v[50:53], v[236:239], v[172:175], v[50:53]
	v_mfma_f32_16x16x32_bf16 v[38:41], v[228:231], v[180:183], v[38:41]
	v_mfma_f32_16x16x32_bf16 v[34:37], v[236:239], v[180:183], v[34:37]
	v_mfma_f32_16x16x32_bf16 v[22:25], v[228:231], v[188:191], v[22:25]
	v_mfma_f32_16x16x32_bf16 v[18:21], v[236:239], v[188:191], v[18:21]
	v_mfma_f32_16x16x32_bf16 v[6:9], v[228:231], v[196:199], v[6:9]
	v_mfma_f32_16x16x32_bf16 v[2:5], v[236:239], v[196:199], v[2:5]
	v_mfma_f32_16x16x32_bf16 v[54:57], v[232:235], v[176:179], v[54:57]
	v_mfma_f32_16x16x32_bf16 v[50:53], v[240:243], v[176:179], v[50:53]
	v_mfma_f32_16x16x32_bf16 v[38:41], v[232:235], v[184:187], v[38:41]
	v_mfma_f32_16x16x32_bf16 v[34:37], v[240:243], v[184:187], v[34:37]
	v_mfma_f32_16x16x32_bf16 v[22:25], v[232:235], v[192:195], v[22:25]
	v_mfma_f32_16x16x32_bf16 v[18:21], v[240:243], v[192:195], v[18:21]
	v_mfma_f32_16x16x32_bf16 v[6:9], v[232:235], v[224:227], v[6:9]
	v_mfma_f32_16x16x32_bf16 v[2:5], v[240:243], v[224:227], v[2:5]
	s_setprio 0
	s_add_i32 s70, 0, 0x18000
	v_add_u32_e32 v161, s70, v153
	s_barrier
	ds_read_b128 v[140:143], v161
	ds_read_b128 v[144:147], v161 offset:1024
	ds_read_b128 v[148:151], v161 offset:2048
	ds_read_b128 v[168:171], v161 offset:3072
	s_add_u32 s0, s50, 0x2c0000
	s_addc_u32 s1, s51, 0
	s_mov_b32 m0, s55
	v_lshl_add_u64 v[220:221], s[0:1], 0, v[134:135]
	ds_read_b128 v[172:175], v155 offset:32768
	ds_read_b128 v[176:179], v155 offset:33792
	ds_read_b128 v[180:183], v155 offset:34816
	ds_read_b128 v[184:187], v155 offset:35840
	ds_read_b128 v[188:191], v155 offset:36864
	ds_read_b128 v[192:195], v155 offset:37888
	ds_read_b128 v[196:199], v155 offset:38912
	ds_read_b128 v[224:227], v155 offset:39936
	global_load_lds_dwordx4 v[220:221], off
	v_lshl_add_u64 v[220:221], s[0:1], 0, v[132:133]
	s_mov_b32 m0, s56
	s_nop 0
	global_load_lds_dwordx4 v[220:221], off
	s_waitcnt lgkmcnt(8)
	s_barrier
	s_waitcnt lgkmcnt(0)
	s_setprio 1
	s_waitcnt lgkmcnt(0)
	v_mfma_f32_16x16x32_bf16 v[126:129], v[140:143], v[172:175], v[126:129]
	v_mfma_f32_16x16x32_bf16 v[122:125], v[148:151], v[172:175], v[122:125]
	v_mfma_f32_16x16x32_bf16 v[110:113], v[140:143], v[180:183], v[110:113]
	v_mfma_f32_16x16x32_bf16 v[106:109], v[148:151], v[180:183], v[106:109]
	v_mfma_f32_16x16x32_bf16 v[94:97], v[140:143], v[188:191], v[94:97]
	v_mfma_f32_16x16x32_bf16 v[90:93], v[148:151], v[188:191], v[90:93]
	v_mfma_f32_16x16x32_bf16 v[78:81], v[140:143], v[196:199], v[78:81]
	v_mfma_f32_16x16x32_bf16 v[74:77], v[148:151], v[196:199], v[74:77]
	v_mfma_f32_16x16x32_bf16 v[126:129], v[144:147], v[176:179], v[126:129]
	v_mfma_f32_16x16x32_bf16 v[122:125], v[168:171], v[176:179], v[122:125]
	v_mfma_f32_16x16x32_bf16 v[110:113], v[144:147], v[184:187], v[110:113]
	v_mfma_f32_16x16x32_bf16 v[106:109], v[168:171], v[184:187], v[106:109]
	v_mfma_f32_16x16x32_bf16 v[94:97], v[144:147], v[192:195], v[94:97]
	v_mfma_f32_16x16x32_bf16 v[90:93], v[168:171], v[192:195], v[90:93]
	v_mfma_f32_16x16x32_bf16 v[78:81], v[144:147], v[224:227], v[78:81]
	v_mfma_f32_16x16x32_bf16 v[74:77], v[168:171], v[224:227], v[74:77]
	s_setprio 0
	s_barrier
	s_add_i32 s50, 0, 0x1c000
	s_add_i32 s0, s70, s52
	v_add_u32_e32 v161, s50, v153
	v_lshl_add_u64 v[156:157], v[156:157], 0, s[94:95]
	s_mov_b32 m0, s0
	ds_read_b128 v[228:231], v161
	ds_read_b128 v[232:235], v161 offset:1024
	ds_read_b128 v[236:239], v161 offset:2048
	ds_read_b128 v[240:243], v161 offset:3072
	global_load_lds_dwordx4 v[156:157], off
	v_lshl_add_u64 v[156:157], v[200:201], 0, s[94:95]
	s_add_i32 m0, s0, 0x2000
	s_nop 0
	global_load_lds_dwordx4 v[156:157], off
	s_barrier
	s_waitcnt lgkmcnt(0)
	s_setprio 1
	s_waitcnt lgkmcnt(0)
	v_mfma_f32_16x16x32_bf16 v[118:121], v[228:231], v[172:175], v[118:121]
	v_mfma_f32_16x16x32_bf16 v[114:117], v[236:239], v[172:175], v[114:117]
	v_mfma_f32_16x16x32_bf16 v[102:105], v[228:231], v[180:183], v[102:105]
	v_mfma_f32_16x16x32_bf16 v[98:101], v[236:239], v[180:183], v[98:101]
	v_mfma_f32_16x16x32_bf16 v[86:89], v[228:231], v[188:191], v[86:89]
	v_mfma_f32_16x16x32_bf16 v[82:85], v[236:239], v[188:191], v[82:85]
	v_mfma_f32_16x16x32_bf16 v[70:73], v[228:231], v[196:199], v[70:73]
	v_mfma_f32_16x16x32_bf16 v[66:69], v[236:239], v[196:199], v[66:69]
	v_mfma_f32_16x16x32_bf16 v[118:121], v[232:235], v[176:179], v[118:121]
	v_mfma_f32_16x16x32_bf16 v[114:117], v[240:243], v[176:179], v[114:117]
	v_mfma_f32_16x16x32_bf16 v[102:105], v[232:235], v[184:187], v[102:105]
	v_mfma_f32_16x16x32_bf16 v[98:101], v[240:243], v[184:187], v[98:101]
	v_mfma_f32_16x16x32_bf16 v[86:89], v[232:235], v[192:195], v[86:89]
	v_mfma_f32_16x16x32_bf16 v[82:85], v[240:243], v[192:195], v[82:85]
	v_mfma_f32_16x16x32_bf16 v[70:73], v[232:235], v[224:227], v[70:73]
	v_mfma_f32_16x16x32_bf16 v[66:69], v[240:243], v[224:227], v[66:69]
	s_setprio 0
	s_mov_b32 m0, s57
	v_lshl_add_u64 v[156:157], v[210:211], 0, s[94:95]
	s_barrier
	ds_read_b128 v[172:175], v155 offset:49152
	ds_read_b128 v[176:179], v155 offset:50176
	ds_read_b128 v[180:183], v155 offset:51200
	ds_read_b128 v[184:187], v155 offset:52224
	ds_read_b128 v[188:191], v155 offset:53248
	ds_read_b128 v[192:195], v155 offset:54272
	ds_read_b128 v[196:199], v155 offset:55296
	ds_read_b128 v[224:227], v155 offset:56320
	global_load_lds_dwordx4 v[156:157], off
	v_lshl_add_u64 v[156:157], v[212:213], 0, s[94:95]
	s_mov_b32 m0, s58
	s_nop 0
	global_load_lds_dwordx4 v[156:157], off
	s_barrier
	s_waitcnt lgkmcnt(0)
	s_setprio 1
	s_waitcnt lgkmcnt(0)
	v_mfma_f32_16x16x32_bf16 v[62:65], v[140:143], v[172:175], v[62:65]
	v_mfma_f32_16x16x32_bf16 v[58:61], v[148:151], v[172:175], v[58:61]
	v_mfma_f32_16x16x32_bf16 v[46:49], v[140:143], v[180:183], v[46:49]
	v_mfma_f32_16x16x32_bf16 v[42:45], v[148:151], v[180:183], v[42:45]
	v_mfma_f32_16x16x32_bf16 v[30:33], v[140:143], v[188:191], v[30:33]
	v_mfma_f32_16x16x32_bf16 v[26:29], v[148:151], v[188:191], v[26:29]
	v_mfma_f32_16x16x32_bf16 v[14:17], v[140:143], v[196:199], v[14:17]
	v_mfma_f32_16x16x32_bf16 v[10:13], v[148:151], v[196:199], v[10:13]
	v_mfma_f32_16x16x32_bf16 v[62:65], v[144:147], v[176:179], v[62:65]
	v_mfma_f32_16x16x32_bf16 v[58:61], v[168:171], v[176:179], v[58:61]
	v_mfma_f32_16x16x32_bf16 v[46:49], v[144:147], v[184:187], v[46:49]
	v_mfma_f32_16x16x32_bf16 v[42:45], v[168:171], v[184:187], v[42:45]
	v_mfma_f32_16x16x32_bf16 v[30:33], v[144:147], v[192:195], v[30:33]
	v_mfma_f32_16x16x32_bf16 v[26:29], v[168:171], v[192:195], v[26:29]
	v_mfma_f32_16x16x32_bf16 v[14:17], v[144:147], v[224:227], v[14:17]
	v_mfma_f32_16x16x32_bf16 v[10:13], v[168:171], v[224:227], v[10:13]
	s_setprio 0
	s_barrier
	s_add_u32 s0, s48, 0x160080
	s_addc_u32 s1, s49, 0
	s_add_i32 s48, s50, s52
	v_lshl_add_u64 v[140:141], s[0:1], 0, v[0:1]
	s_mov_b32 m0, s48
	s_nop 0
	global_load_lds_dwordx4 v[140:141], off
	v_lshl_add_u64 v[140:141], s[0:1], 0, v[130:131]
	s_add_i32 m0, s48, 0x2000
	s_nop 0
	global_load_lds_dwordx4 v[140:141], off
	s_waitcnt vmcnt(6)
	s_barrier
	s_setprio 1
	v_mfma_f32_16x16x32_bf16 v[54:57], v[228:231], v[172:175], v[54:57]
	v_mfma_f32_16x16x32_bf16 v[50:53], v[236:239], v[172:175], v[50:53]
	v_mfma_f32_16x16x32_bf16 v[38:41], v[228:231], v[180:183], v[38:41]
	v_mfma_f32_16x16x32_bf16 v[34:37], v[236:239], v[180:183], v[34:37]
	v_mfma_f32_16x16x32_bf16 v[22:25], v[228:231], v[188:191], v[22:25]
	v_mfma_f32_16x16x32_bf16 v[18:21], v[236:239], v[188:191], v[18:21]
	v_mfma_f32_16x16x32_bf16 v[6:9], v[228:231], v[196:199], v[6:9]
	v_mfma_f32_16x16x32_bf16 v[2:5], v[236:239], v[196:199], v[2:5]
	v_mfma_f32_16x16x32_bf16 v[54:57], v[232:235], v[176:179], v[54:57]
	v_mfma_f32_16x16x32_bf16 v[50:53], v[240:243], v[176:179], v[50:53]
	v_mfma_f32_16x16x32_bf16 v[38:41], v[232:235], v[184:187], v[38:41]
	v_mfma_f32_16x16x32_bf16 v[34:37], v[240:243], v[184:187], v[34:37]
	v_mfma_f32_16x16x32_bf16 v[22:25], v[232:235], v[192:195], v[22:25]
	v_mfma_f32_16x16x32_bf16 v[18:21], v[240:243], v[192:195], v[18:21]
	v_mfma_f32_16x16x32_bf16 v[6:9], v[232:235], v[224:227], v[6:9]
	v_mfma_f32_16x16x32_bf16 v[2:5], v[240:243], v[224:227], v[2:5]
	s_setprio 0
	s_add_u32 s13, s13, 0x100
	s_addc_u32 s68, s68, 0
	s_cmp_ge_i32 s69, s39
	s_mov_b64 s[0:1], s[46:47]
	s_mov_b32 s48, s69
	s_barrier
	s_cbranch_scc0 .LBB0_37
	s_cmp_eq_u32 s65, 2
	s_cbranch_scc1 .Lepi10_orig
	v_readlane_b32 s90, v255, 17
	v_readlane_b32 s91, v255, 18
	v_readlane_b32 s96, v255, 19
	v_readlane_b32 s97, v255, 20
	v_lshl_or_b32 v156, s66, 8, v154
	v_lshlrev_b32_e32 v156, 2, v156
	v_lshl_add_u32 v157, v152, 13, v156
	s_lshl_b32 s72, s67, 21
	s_add_u32 s74, s22, s72
	s_addc_u32 s75, s23, 0
	s_add_u32 s76, s22, s72
	s_addc_u32 s77, s23, 0
	s_lshr_b32 s73, s67, 3
	s_mul_i32 s73, s73, 0xc000
	s_add_u32 s73, s73, 0xa000
	s_add_u32 s70, s90, s73
	s_addc_u32 s71, s91, 0
	global_load_dwordx4 v[140:143], v156, s[70:71]
	global_load_dwordx4 v[144:147], v156, s[70:71] offset:64
	global_load_dwordx4 v[148:151], v156, s[70:71] offset:512
	global_load_dwordx4 v[168:171], v156, s[70:71] offset:576
	global_load_dwordx4 v[224:227], v157, s[74:75] nt
	global_load_dwordx4 v[228:231], v157, s[74:75] offset:64 nt
	global_load_dwordx4 v[232:235], v157, s[74:75] offset:512 nt
	global_load_dwordx4 v[236:239], v157, s[74:75] offset:576 nt
	s_add_u32 s74, s74, 0x20000
	s_addc_u32 s75, s75, 0
	global_load_dwordx4 v[240:243], v157, s[74:75] nt
	global_load_dwordx4 v[244:247], v157, s[74:75] offset:64 nt
	s_waitcnt vmcnt(5)
	v_pk_fma_f32 v[128:129], v[128:129], v[142:143], v[226:227]
	v_pk_fma_f32 v[126:127], v[126:127], v[140:141], v[224:225]
	global_store_dwordx4 v157, v[126:129], s[76:77] nt
	global_load_dwordx4 v[224:227], v157, s[74:75] offset:512 nt
	s_waitcnt vmcnt(6)
	v_pk_fma_f32 v[124:125], v[124:125], v[146:147], v[230:231]
	v_pk_fma_f32 v[122:123], v[122:123], v[144:145], v[228:229]
	global_store_dwordx4 v157, v[122:125], s[76:77] offset:64 nt
	global_load_dwordx4 v[228:231], v157, s[74:75] offset:576 nt
	s_waitcnt vmcnt(7)
	v_pk_fma_f32 v[120:121], v[120:121], v[150:151], v[234:235]
	v_pk_fma_f32 v[118:119], v[118:119], v[148:149], v[232:233]
	global_store_dwordx4 v157, v[118:121], s[76:77] offset:512 nt
	s_add_u32 s74, s74, 0x20000
	s_addc_u32 s75, s75, 0
	global_load_dwordx4 v[232:235], v157, s[74:75] nt
	s_waitcnt vmcnt(8)
	v_pk_fma_f32 v[116:117], v[116:117], v[170:171], v[238:239]
	v_pk_fma_f32 v[114:115], v[114:115], v[168:169], v[236:237]
	global_store_dwordx4 v157, v[114:117], s[76:77] offset:576 nt
	global_load_dwordx4 v[236:239], v157, s[74:75] offset:64 nt
	s_add_u32 s76, s76, 0x20000
	s_addc_u32 s77, s77, 0
	s_waitcnt vmcnt(9)
	v_pk_fma_f32 v[112:113], v[112:113], v[142:143], v[242:243]
	v_pk_fma_f32 v[110:111], v[110:111], v[140:141], v[240:241]
	global_store_dwordx4 v157, v[110:113], s[76:77] nt
	global_load_dwordx4 v[240:243], v157, s[74:75] offset:512 nt
	s_waitcnt vmcnt(10)
	v_pk_fma_f32 v[108:109], v[108:109], v[146:147], v[246:247]
	v_pk_fma_f32 v[106:107], v[106:107], v[144:145], v[244:245]
	global_store_dwordx4 v157, v[106:109], s[76:77] offset:64 nt
	global_load_dwordx4 v[244:247], v157, s[74:75] offset:576 nt
	s_waitcnt vmcnt(10)
	v_pk_fma_f32 v[104:105], v[104:105], v[150:151], v[226:227]
	v_pk_fma_f32 v[102:103], v[102:103], v[148:149], v[224:225]
	global_store_dwordx4 v157, v[102:105], s[76:77] offset:512 nt
	s_add_u32 s74, s74, 0x20000
	s_addc_u32 s75, s75, 0
	global_load_dwordx4 v[224:227], v157, s[74:75] nt
	s_waitcnt vmcnt(10)
	v_pk_fma_f32 v[100:101], v[100:101], v[170:171], v[230:231]
	v_pk_fma_f32 v[98:99], v[98:99], v[168:169], v[228:229]
	global_store_dwordx4 v157, v[98:101], s[76:77] offset:576 nt
	global_load_dwordx4 v[228:231], v157, s[74:75] offset:64 nt
	s_add_u32 s76, s76, 0x20000
	s_addc_u32 s77, s77, 0
	s_waitcnt vmcnt(10)
	v_pk_fma_f32 v[96:97], v[96:97], v[142:143], v[234:235]
	v_pk_fma_f32 v[94:95], v[94:95], v[140:141], v[232:233]
	global_store_dwordx4 v157, v[94:97], s[76:77] nt
	global_load_dwordx4 v[232:235], v157, s[74:75] offset:512 nt
	s_waitcnt vmcnt(10)
	v_pk_fma_f32 v[92:93], v[92:93], v[146:147], v[238:239]
	v_pk_fma_f32 v[90:91], v[90:91], v[144:145], v[236:237]
	global_store_dwordx4 v157, v[90:93], s[76:77] offset:64 nt
	global_load_dwordx4 v[236:239], v157, s[74:75] offset:576 nt
	s_waitcnt vmcnt(10)
	v_pk_fma_f32 v[88:89], v[88:89], v[150:151], v[242:243]
	v_pk_fma_f32 v[86:87], v[86:87], v[148:149], v[240:241]
	global_store_dwordx4 v157, v[86:89], s[76:77] offset:512 nt
	s_add_u32 s74, s74, 0xa0000
	s_addc_u32 s75, s75, 0
	global_load_dwordx4 v[240:243], v157, s[74:75] nt
	s_waitcnt vmcnt(10)
	v_pk_fma_f32 v[84:85], v[84:85], v[170:171], v[246:247]
	v_pk_fma_f32 v[82:83], v[82:83], v[168:169], v[244:245]
	global_store_dwordx4 v157, v[82:85], s[76:77] offset:576 nt
	global_load_dwordx4 v[244:247], v157, s[74:75] offset:64 nt
	s_add_u32 s76, s76, 0x20000
	s_addc_u32 s77, s77, 0
	s_waitcnt vmcnt(10)
	v_pk_fma_f32 v[80:81], v[80:81], v[142:143], v[226:227]
	v_pk_fma_f32 v[78:79], v[78:79], v[140:141], v[224:225]
	global_store_dwordx4 v157, v[78:81], s[76:77] nt
	global_load_dwordx4 v[224:227], v157, s[74:75] offset:512 nt
	s_waitcnt vmcnt(10)
	v_pk_fma_f32 v[76:77], v[76:77], v[146:147], v[230:231]
	v_pk_fma_f32 v[74:75], v[74:75], v[144:145], v[228:229]
	global_store_dwordx4 v157, v[74:77], s[76:77] offset:64 nt
	global_load_dwordx4 v[228:231], v157, s[74:75] offset:576 nt
	s_waitcnt vmcnt(10)
	v_pk_fma_f32 v[72:73], v[72:73], v[150:151], v[234:235]
	v_pk_fma_f32 v[70:71], v[70:71], v[148:149], v[232:233]
	global_store_dwordx4 v157, v[70:73], s[76:77] offset:512 nt
	s_add_u32 s74, s74, 0x20000
	s_addc_u32 s75, s75, 0
	global_load_dwordx4 v[232:235], v157, s[74:75] nt
	s_waitcnt vmcnt(10)
	v_pk_fma_f32 v[68:69], v[68:69], v[170:171], v[238:239]
	v_pk_fma_f32 v[66:67], v[66:67], v[168:169], v[236:237]
	global_store_dwordx4 v157, v[66:69], s[76:77] offset:576 nt
	global_load_dwordx4 v[236:239], v157, s[74:75] offset:64 nt
	s_add_u32 s76, s76, 0xa0000
	s_addc_u32 s77, s77, 0
	s_waitcnt vmcnt(10)
	v_pk_fma_f32 v[64:65], v[64:65], v[142:143], v[242:243]
	v_pk_fma_f32 v[62:63], v[62:63], v[140:141], v[240:241]
	global_store_dwordx4 v157, v[62:65], s[76:77] nt
	global_load_dwordx4 v[240:243], v157, s[74:75] offset:512 nt
	s_waitcnt vmcnt(10)
	v_pk_fma_f32 v[60:61], v[60:61], v[146:147], v[246:247]
	v_pk_fma_f32 v[58:59], v[58:59], v[144:145], v[244:245]
	global_store_dwordx4 v157, v[58:61], s[76:77] offset:64 nt
	global_load_dwordx4 v[244:247], v157, s[74:75] offset:576 nt
	s_waitcnt vmcnt(10)
	v_pk_fma_f32 v[56:57], v[56:57], v[150:151], v[226:227]
	v_pk_fma_f32 v[54:55], v[54:55], v[148:149], v[224:225]
	global_store_dwordx4 v157, v[54:57], s[76:77] offset:512 nt
	s_add_u32 s74, s74, 0x20000
	s_addc_u32 s75, s75, 0
	global_load_dwordx4 v[224:227], v157, s[74:75] nt
	s_waitcnt vmcnt(10)
	v_pk_fma_f32 v[52:53], v[52:53], v[170:171], v[230:231]
	v_pk_fma_f32 v[50:51], v[50:51], v[168:169], v[228:229]
	global_store_dwordx4 v157, v[50:53], s[76:77] offset:576 nt
	global_load_dwordx4 v[228:231], v157, s[74:75] offset:64 nt
	s_add_u32 s76, s76, 0x20000
	s_addc_u32 s77, s77, 0
	s_waitcnt vmcnt(10)
	v_pk_fma_f32 v[48:49], v[48:49], v[142:143], v[234:235]
	v_pk_fma_f32 v[46:47], v[46:47], v[140:141], v[232:233]
	global_store_dwordx4 v157, v[46:49], s[76:77] nt
	global_load_dwordx4 v[232:235], v157, s[74:75] offset:512 nt
	s_waitcnt vmcnt(10)
	v_pk_fma_f32 v[44:45], v[44:45], v[146:147], v[238:239]
	v_pk_fma_f32 v[42:43], v[42:43], v[144:145], v[236:237]
	global_store_dwordx4 v157, v[42:45], s[76:77] offset:64 nt
	global_load_dwordx4 v[236:239], v157, s[74:75] offset:576 nt
	s_waitcnt vmcnt(10)
	v_pk_fma_f32 v[40:41], v[40:41], v[150:151], v[242:243]
	v_pk_fma_f32 v[38:39], v[38:39], v[148:149], v[240:241]
	global_store_dwordx4 v157, v[38:41], s[76:77] offset:512 nt
	s_add_u32 s74, s74, 0x20000
	s_addc_u32 s75, s75, 0
	global_load_dwordx4 v[240:243], v157, s[74:75] nt
	s_waitcnt vmcnt(10)
	v_pk_fma_f32 v[36:37], v[36:37], v[170:171], v[246:247]
	v_pk_fma_f32 v[34:35], v[34:35], v[168:169], v[244:245]
	global_store_dwordx4 v157, v[34:37], s[76:77] offset:576 nt
	global_load_dwordx4 v[244:247], v157, s[74:75] offset:64 nt
	s_add_u32 s76, s76, 0x20000
	s_addc_u32 s77, s77, 0
	s_waitcnt vmcnt(10)
	v_pk_fma_f32 v[32:33], v[32:33], v[142:143], v[226:227]
	v_pk_fma_f32 v[30:31], v[30:31], v[140:141], v[224:225]
	global_store_dwordx4 v157, v[30:33], s[76:77] nt
	global_load_dwordx4 v[224:227], v157, s[74:75] offset:512 nt
	s_waitcnt vmcnt(10)
	v_pk_fma_f32 v[28:29], v[28:29], v[146:147], v[230:231]
	v_pk_fma_f32 v[26:27], v[26:27], v[144:145], v[228:229]
	global_store_dwordx4 v157, v[26:29], s[76:77] offset:64 nt
	global_load_dwordx4 v[228:231], v157, s[74:75] offset:576 nt
	s_waitcnt vmcnt(10)
	v_pk_fma_f32 v[24:25], v[24:25], v[150:151], v[234:235]
	v_pk_fma_f32 v[22:23], v[22:23], v[148:149], v[232:233]
	global_store_dwordx4 v157, v[22:25], s[76:77] offset:512 nt
	s_waitcnt vmcnt(9)
	v_pk_fma_f32 v[20:21], v[20:21], v[170:171], v[238:239]
	v_pk_fma_f32 v[18:19], v[18:19], v[168:169], v[236:237]
	global_store_dwordx4 v157, v[18:21], s[76:77] offset:576 nt
	s_add_u32 s76, s76, 0x20000
	s_addc_u32 s77, s77, 0
	s_waitcnt vmcnt(8)
	v_pk_fma_f32 v[16:17], v[16:17], v[142:143], v[242:243]
	v_pk_fma_f32 v[14:15], v[14:15], v[140:141], v[240:241]
	global_store_dwordx4 v157, v[14:17], s[76:77] nt
	s_waitcnt vmcnt(7)
	v_pk_fma_f32 v[12:13], v[12:13], v[146:147], v[246:247]
	v_pk_fma_f32 v[10:11], v[10:11], v[144:145], v[244:245]
	global_store_dwordx4 v157, v[10:13], s[76:77] offset:64 nt
	s_waitcnt vmcnt(6)
	v_pk_fma_f32 v[8:9], v[8:9], v[150:151], v[226:227]
	v_pk_fma_f32 v[6:7], v[6:7], v[148:149], v[224:225]
	global_store_dwordx4 v157, v[6:9], s[76:77] offset:512 nt
	s_waitcnt vmcnt(5)
	v_pk_fma_f32 v[4:5], v[4:5], v[170:171], v[230:231]
	v_pk_fma_f32 v[2:3], v[2:3], v[168:169], v[228:229]
	global_store_dwordx4 v157, v[2:5], s[76:77] offset:576 nt
	s_branch .LBB0_24
.Lepi10_orig:
	v_lshl_or_b32 v140, s66, 8, v154
	v_lshl_add_u32 v142, s67, 8, v152
	v_ashrrev_i32_e32 v141, 31, v140
	s_movk_i32 s0, 0x2080
	v_ashrrev_i32_e32 v156, 11, v142
	v_cmp_gt_i32_e32 vcc, s0, v142
	v_lshlrev_b64 v[144:145], 2, v[140:141]
	v_ashrrev_i32_e32 v143, 31, v142
	s_and_saveexec_b64 s[46:47], vcc
	v_readlane_b32 s90, v255, 17
	v_readlane_b32 s96, v255, 19
	v_readlane_b32 s91, v255, 18
	v_readlane_b32 s97, v255, 20
	s_cbranch_execz .LBB0_55
	v_add_u32_e32 v150, 0xffffe000, v142
	v_lshrrev_b32_e32 v146, 4, v150
	s_movk_i32 s0, 0x2000
	v_add_u32_e32 v146, 4, v146
	v_cmp_gt_i32_e32 vcc, s0, v142
	s_mov_b32 s0, 0xc000
	s_cmp_lg_u32 s65, 2
	v_cndmask_b32_e32 v148, v146, v156, vcc
	v_mov_b64_e32 v[146:147], s[90:91]
	v_mad_i64_i32 v[146:147], s[0:1], v148, s0, v[146:147]
	v_lshl_add_u64 v[146:147], v[146:147], 0, v[144:145]
	s_mov_b64 s[0:1], 0xa000
	v_lshl_add_u64 v[148:149], v[146:147], 0, s[0:1]
	v_lshlrev_b64 v[146:147], 13, v[142:143]
	v_lshl_add_u64 v[146:147], s[22:23], 0, v[146:147]
	s_cselect_b64 s[48:49], -1, 0
	v_lshl_add_u64 v[146:147], v[146:147], 0, v[144:145]
	s_mov_b64 s[0:1], -1
	s_and_b64 vcc, exec, s[48:49]
	s_cbranch_vccz .LBB0_41
	global_load_dwordx4 v[168:171], v[146:147], off nt
	global_load_dwordx4 v[172:175], v[148:149], off
	s_mov_b64 s[0:1], 0
	s_waitcnt vmcnt(0)
	v_pk_fma_f32 v[170:171], v[128:129], v[174:175], v[170:171]
	v_pk_fma_f32 v[168:169], v[126:127], v[172:173], v[168:169]
	global_store_dwordx4 v[146:147], v[168:171], off nt

.LBB0_256:
	v_ashrrev_i32_e32 v0, 9, v9
	v_and_b32_e32 v3, 0x7fc, v8
	v_add_u32_e32 v2, s12, v0
	v_lshlrev_b32_e32 v0, 2, v3
	v_ashrrev_i32_e32 v3, 31, v2
	v_lshl_add_u64 v[4:5], s[96:97], 0, v[0:1]
	v_lshlrev_b64 v[6:7], 13, v[2:3]
	v_lshl_add_u64 v[10:11], v[4:5], 0, v[6:7]
	v_lshl_add_u64 v[6:7], s[22:23], 0, v[6:7]
	v_lshl_add_u64 v[18:19], v[6:7], 0, v[0:1]
	v_add_co_u32_e32 v2, vcc, 0xfc000000, v10
	s_nop 1
	v_addc_co_u32_e32 v3, vcc, -1, v11, vcc
	global_load_dwordx4 v[20:23], v[2:3], off
	v_add_co_u32_e32 v2, vcc, 0xfc100000, v10
	s_nop 1
	v_addc_co_u32_e32 v3, vcc, -1, v11, vcc
	global_load_dwordx4 v[24:27], v[2:3], off
	v_add_co_u32_e32 v2, vcc, 0xfc200000, v10
	s_nop 1
	v_addc_co_u32_e32 v3, vcc, -1, v11, vcc
	global_load_dwordx4 v[28:31], v[2:3], off
	v_add_co_u32_e32 v2, vcc, 0xfc300000, v10
	s_nop 1
	v_addc_co_u32_e32 v3, vcc, -1, v11, vcc
	global_load_dwordx4 v[32:35], v[2:3], off
	v_add_co_u32_e32 v2, vcc, 0xfc400000, v10
	s_nop 1
	v_addc_co_u32_e32 v3, vcc, -1, v11, vcc
	global_load_dwordx4 v[36:39], v[2:3], off
	v_add_co_u32_e32 v2, vcc, 0xfc500000, v10
	s_nop 1
	v_addc_co_u32_e32 v3, vcc, -1, v11, vcc
	global_load_dwordx4 v[40:43], v[2:3], off
	v_add_co_u32_e32 v2, vcc, 0xfc600000, v10
	s_nop 1
	v_addc_co_u32_e32 v3, vcc, -1, v11, vcc
	global_load_dwordx4 v[44:47], v[2:3], off
	v_add_co_u32_e32 v2, vcc, 0xfc700000, v10
	s_nop 1
	v_addc_co_u32_e32 v3, vcc, -1, v11, vcc
	global_load_dwordx4 v[48:51], v[2:3], off
	global_load_dwordx4 v[52:55], v0, s[48:49]
	global_load_dwordx4 v[56:59], v[18:19], off
	s_movk_i32 s13, 0x1dff
	v_add_u32_e32 v8, 0x800, v8
	v_cmp_lt_i32_e32 vcc, s13, v9
	s_or_b64 s[50:51], vcc, s[50:51]
	v_add_u32_e32 v9, 0x200, v9
	s_waitcnt vmcnt(9)
	v_pk_add_f32 v[14:15], v[20:21], 0 op_sel_hi:[1,0]
	v_pk_add_f32 v[12:13], v[22:23], 0 op_sel_hi:[1,0]
	s_waitcnt vmcnt(8)
	v_pk_add_f32 v[14:15], v[14:15], v[24:25]
	v_pk_add_f32 v[12:13], v[12:13], v[26:27]
	s_waitcnt vmcnt(7)
	v_pk_add_f32 v[14:15], v[14:15], v[28:29]
	v_pk_add_f32 v[12:13], v[12:13], v[30:31]
	s_waitcnt vmcnt(6)
	v_pk_add_f32 v[14:15], v[14:15], v[32:33]
	v_pk_add_f32 v[12:13], v[12:13], v[34:35]
	s_waitcnt vmcnt(5)
	v_pk_add_f32 v[14:15], v[14:15], v[36:37]
	v_pk_add_f32 v[12:13], v[12:13], v[38:39]
	s_waitcnt vmcnt(4)
	v_pk_add_f32 v[14:15], v[14:15], v[40:41]
	v_pk_add_f32 v[12:13], v[12:13], v[42:43]
	s_waitcnt vmcnt(3)
	v_pk_add_f32 v[14:15], v[14:15], v[44:45]
	v_pk_add_f32 v[12:13], v[12:13], v[46:47]
	s_waitcnt vmcnt(2)
	v_pk_add_f32 v[14:15], v[14:15], v[48:49]
	v_pk_add_f32 v[12:13], v[12:13], v[50:51]
	s_waitcnt vmcnt(0)
	v_pk_fma_f32 v[6:7], v[12:13], v[54:55], v[58:59]
	v_pk_fma_f32 v[4:5], v[14:15], v[52:53], v[56:57]
	global_store_dwordx4 v[18:19], v[4:7], off
	s_andn2_b64 exec, exec, s[50:51]
	s_cbranch_execnz .LBB0_256

.LBB0_282:
	s_add_i32 s67, s50, 2
	s_add_u32 s51, s0, 0xfff80080
	s_addc_u32 s52, s1, -1
	s_add_i32 s68, 0, 0x10000
	v_add_u32_e32 v148, s68, v153
	ds_read_b128 v[136:139], v148
	ds_read_b128 v[140:143], v148 offset:1024
	ds_read_b128 v[144:147], v148 offset:2048
	ds_read_b128 v[148:151], v148 offset:3072
	s_cmp_eq_u32 s12, s50
	s_cselect_b32 s50, s48, s13
	s_cselect_b32 s53, s47, s52
	s_cselect_b32 s52, s46, s51
	s_cselect_b32 s51, s49, s66
	v_lshl_add_u64 v[156:157], s[0:1], 0, v[132:133]
	s_add_i32 m0, s55, 0xc000
	ds_read_b128 v[168:171], v155
	ds_read_b128 v[172:175], v155 offset:1024
	ds_read_b128 v[176:179], v155 offset:2048
	ds_read_b128 v[180:183], v155 offset:3072
	ds_read_b128 v[184:187], v155 offset:4096
	ds_read_b128 v[188:191], v155 offset:5120
	ds_read_b128 v[192:195], v155 offset:6144
	ds_read_b128 v[196:199], v155 offset:7168
	global_load_lds_dwordx4 v[156:157], off
	v_lshl_add_u64 v[156:157], s[0:1], 0, v[134:135]
	s_add_i32 m0, s55, 0xe000
	s_nop 0
	global_load_lds_dwordx4 v[156:157], off
	s_waitcnt lgkmcnt(8)
	s_barrier
	s_waitcnt lgkmcnt(0)
	s_setprio 1
	s_waitcnt lgkmcnt(0)
	v_mfma_f32_16x16x32_bf16 v[126:129], v[136:139], v[168:171], v[126:129]
	v_mfma_f32_16x16x32_bf16 v[122:125], v[144:147], v[168:171], v[122:125]
	v_mfma_f32_16x16x32_bf16 v[110:113], v[136:139], v[176:179], v[110:113]
	v_mfma_f32_16x16x32_bf16 v[106:109], v[144:147], v[176:179], v[106:109]
	v_mfma_f32_16x16x32_bf16 v[94:97], v[136:139], v[184:187], v[94:97]
	v_mfma_f32_16x16x32_bf16 v[90:93], v[144:147], v[184:187], v[90:93]
	v_mfma_f32_16x16x32_bf16 v[78:81], v[136:139], v[192:195], v[78:81]
	v_mfma_f32_16x16x32_bf16 v[74:77], v[144:147], v[192:195], v[74:77]
	v_mfma_f32_16x16x32_bf16 v[126:129], v[140:143], v[172:175], v[126:129]
	v_mfma_f32_16x16x32_bf16 v[122:125], v[148:151], v[172:175], v[122:125]
	v_mfma_f32_16x16x32_bf16 v[110:113], v[140:143], v[180:183], v[110:113]
	v_mfma_f32_16x16x32_bf16 v[106:109], v[148:151], v[180:183], v[106:109]
	v_mfma_f32_16x16x32_bf16 v[94:97], v[140:143], v[188:191], v[94:97]
	v_mfma_f32_16x16x32_bf16 v[90:93], v[148:151], v[188:191], v[90:93]
	v_mfma_f32_16x16x32_bf16 v[78:81], v[140:143], v[196:199], v[78:81]
	v_mfma_f32_16x16x32_bf16 v[74:77], v[148:151], v[196:199], v[74:77]
	s_setprio 0
	s_barrier
	s_add_i32 s70, 0, 0x14000
	v_add_u32_e32 v156, s70, v153
	s_add_i32 s68, s68, s54
	ds_read_b128 v[224:227], v156
	ds_read_b128 v[228:231], v156 offset:1024
	ds_read_b128 v[232:235], v156 offset:2048
	ds_read_b128 v[236:239], v156 offset:3072
	v_lshl_add_u64 v[156:157], s[50:51], 0, v[0:1]
	s_mov_b32 m0, s68
	v_lshl_add_u64 v[200:201], s[50:51], 0, v[130:131]
	global_load_lds_dwordx4 v[156:157], off
	s_add_i32 m0, s68, 0x2000
	s_nop 0
	global_load_lds_dwordx4 v[200:201], off
	s_barrier
	s_waitcnt lgkmcnt(0)
	s_setprio 1
	s_waitcnt lgkmcnt(0)
	v_mfma_f32_16x16x32_bf16 v[118:121], v[224:227], v[168:171], v[118:121]
	v_mfma_f32_16x16x32_bf16 v[114:117], v[232:235], v[168:171], v[114:117]
	v_mfma_f32_16x16x32_bf16 v[102:105], v[224:227], v[176:179], v[102:105]
	v_mfma_f32_16x16x32_bf16 v[98:101], v[232:235], v[176:179], v[98:101]
	v_mfma_f32_16x16x32_bf16 v[86:89], v[224:227], v[184:187], v[86:89]
	v_mfma_f32_16x16x32_bf16 v[82:85], v[232:235], v[184:187], v[82:85]
	v_mfma_f32_16x16x32_bf16 v[70:73], v[224:227], v[192:195], v[70:73]
	v_mfma_f32_16x16x32_bf16 v[66:69], v[232:235], v[192:195], v[66:69]
	v_mfma_f32_16x16x32_bf16 v[118:121], v[228:231], v[172:175], v[118:121]
	v_mfma_f32_16x16x32_bf16 v[114:117], v[236:239], v[172:175], v[114:117]
	v_mfma_f32_16x16x32_bf16 v[102:105], v[228:231], v[180:183], v[102:105]
	v_mfma_f32_16x16x32_bf16 v[98:101], v[236:239], v[180:183], v[98:101]
	v_mfma_f32_16x16x32_bf16 v[86:89], v[228:231], v[188:191], v[86:89]
	v_mfma_f32_16x16x32_bf16 v[82:85], v[236:239], v[188:191], v[82:85]
	v_mfma_f32_16x16x32_bf16 v[70:73], v[228:231], v[196:199], v[70:73]
	v_mfma_f32_16x16x32_bf16 v[66:69], v[236:239], v[196:199], v[66:69]
	s_setprio 0
	s_mov_b32 m0, s55
	v_lshl_add_u64 v[210:211], s[52:53], 0, v[0:1]
	s_barrier
	ds_read_b128 v[168:171], v155 offset:16384
	ds_read_b128 v[172:175], v155 offset:17408
	ds_read_b128 v[176:179], v155 offset:18432
	ds_read_b128 v[180:183], v155 offset:19456
	ds_read_b128 v[184:187], v155 offset:20480
	ds_read_b128 v[188:191], v155 offset:21504
	ds_read_b128 v[192:195], v155 offset:22528
	ds_read_b128 v[196:199], v155 offset:23552
	global_load_lds_dwordx4 v[210:211], off
	v_lshl_add_u64 v[212:213], s[52:53], 0, v[130:131]
	s_mov_b32 m0, s56
	s_nop 0
	global_load_lds_dwordx4 v[212:213], off
	s_barrier
	s_waitcnt lgkmcnt(0)
	s_setprio 1
	s_waitcnt lgkmcnt(0)
	v_mfma_f32_16x16x32_bf16 v[62:65], v[136:139], v[168:171], v[62:65]
	v_mfma_f32_16x16x32_bf16 v[58:61], v[144:147], v[168:171], v[58:61]
	v_mfma_f32_16x16x32_bf16 v[46:49], v[136:139], v[176:179], v[46:49]
	v_mfma_f32_16x16x32_bf16 v[42:45], v[144:147], v[176:179], v[42:45]
	v_mfma_f32_16x16x32_bf16 v[30:33], v[136:139], v[184:187], v[30:33]
	v_mfma_f32_16x16x32_bf16 v[26:29], v[144:147], v[184:187], v[26:29]
	v_mfma_f32_16x16x32_bf16 v[14:17], v[136:139], v[192:195], v[14:17]
	v_mfma_f32_16x16x32_bf16 v[10:13], v[144:147], v[192:195], v[10:13]
	v_mfma_f32_16x16x32_bf16 v[62:65], v[140:143], v[172:175], v[62:65]
	v_mfma_f32_16x16x32_bf16 v[58:61], v[148:151], v[172:175], v[58:61]
	v_mfma_f32_16x16x32_bf16 v[46:49], v[140:143], v[180:183], v[46:49]
	v_mfma_f32_16x16x32_bf16 v[42:45], v[148:151], v[180:183], v[42:45]
	v_mfma_f32_16x16x32_bf16 v[30:33], v[140:143], v[188:191], v[30:33]
	v_mfma_f32_16x16x32_bf16 v[26:29], v[148:151], v[188:191], v[26:29]
	v_mfma_f32_16x16x32_bf16 v[14:17], v[140:143], v[196:199], v[14:17]
	v_mfma_f32_16x16x32_bf16 v[10:13], v[148:151], v[196:199], v[10:13]
	s_setprio 0
	s_barrier
	s_add_u32 s68, s50, 0x80000
	s_addc_u32 s69, s51, 0
	s_add_i32 s70, s70, s54
	v_lshl_add_u64 v[136:137], s[68:69], 0, v[0:1]
	s_mov_b32 m0, s70
	s_nop 0
	global_load_lds_dwordx4 v[136:137], off
	v_lshl_add_u64 v[136:137], s[68:69], 0, v[130:131]
	s_add_i32 m0, s70, 0x2000
	s_nop 0
	global_load_lds_dwordx4 v[136:137], off
	s_waitcnt vmcnt(6)
	s_barrier
	s_setprio 1
	v_mfma_f32_16x16x32_bf16 v[54:57], v[224:227], v[168:171], v[54:57]
	v_mfma_f32_16x16x32_bf16 v[50:53], v[232:235], v[168:171], v[50:53]
	v_mfma_f32_16x16x32_bf16 v[38:41], v[224:227], v[176:179], v[38:41]
	v_mfma_f32_16x16x32_bf16 v[34:37], v[232:235], v[176:179], v[34:37]
	v_mfma_f32_16x16x32_bf16 v[22:25], v[224:227], v[184:187], v[22:25]
	v_mfma_f32_16x16x32_bf16 v[18:21], v[232:235], v[184:187], v[18:21]
	v_mfma_f32_16x16x32_bf16 v[6:9], v[224:227], v[192:195], v[6:9]
	v_mfma_f32_16x16x32_bf16 v[2:5], v[232:235], v[192:195], v[2:5]
	v_mfma_f32_16x16x32_bf16 v[54:57], v[228:231], v[172:175], v[54:57]
	v_mfma_f32_16x16x32_bf16 v[50:53], v[236:239], v[172:175], v[50:53]
	v_mfma_f32_16x16x32_bf16 v[38:41], v[228:231], v[180:183], v[38:41]
	v_mfma_f32_16x16x32_bf16 v[34:37], v[236:239], v[180:183], v[34:37]
	v_mfma_f32_16x16x32_bf16 v[22:25], v[228:231], v[188:191], v[22:25]
	v_mfma_f32_16x16x32_bf16 v[18:21], v[236:239], v[188:191], v[18:21]
	v_mfma_f32_16x16x32_bf16 v[6:9], v[228:231], v[196:199], v[6:9]
	v_mfma_f32_16x16x32_bf16 v[2:5], v[236:239], v[196:199], v[2:5]
	s_setprio 0
	s_add_i32 s68, 0, 0x18000
	v_add_u32_e32 v148, s68, v153
	s_barrier
	ds_read_b128 v[136:139], v148
	ds_read_b128 v[140:143], v148 offset:1024
	ds_read_b128 v[144:147], v148 offset:2048
	ds_read_b128 v[148:151], v148 offset:3072
	s_add_u32 s52, s52, 0x80000
	s_addc_u32 s53, s53, 0
	s_mov_b32 m0, s57
	v_lshl_add_u64 v[220:221], s[52:53], 0, v[0:1]
	ds_read_b128 v[168:171], v155 offset:32768
	ds_read_b128 v[172:175], v155 offset:33792
	ds_read_b128 v[176:179], v155 offset:34816
	ds_read_b128 v[180:183], v155 offset:35840
	ds_read_b128 v[184:187], v155 offset:36864
	ds_read_b128 v[188:191], v155 offset:37888
	ds_read_b128 v[192:195], v155 offset:38912
	ds_read_b128 v[196:199], v155 offset:39936
	global_load_lds_dwordx4 v[220:221], off
	v_lshl_add_u64 v[220:221], s[52:53], 0, v[130:131]
	s_mov_b32 m0, s58
	s_nop 0
	global_load_lds_dwordx4 v[220:221], off
	s_waitcnt lgkmcnt(8)
	s_barrier
	s_waitcnt lgkmcnt(0)
	s_setprio 1
	s_waitcnt lgkmcnt(0)
	v_mfma_f32_16x16x32_bf16 v[126:129], v[136:139], v[168:171], v[126:129]
	v_mfma_f32_16x16x32_bf16 v[122:125], v[144:147], v[168:171], v[122:125]
	v_mfma_f32_16x16x32_bf16 v[110:113], v[136:139], v[176:179], v[110:113]
	v_mfma_f32_16x16x32_bf16 v[106:109], v[144:147], v[176:179], v[106:109]
	v_mfma_f32_16x16x32_bf16 v[94:97], v[136:139], v[184:187], v[94:97]
	v_mfma_f32_16x16x32_bf16 v[90:93], v[144:147], v[184:187], v[90:93]
	v_mfma_f32_16x16x32_bf16 v[78:81], v[136:139], v[192:195], v[78:81]
	v_mfma_f32_16x16x32_bf16 v[74:77], v[144:147], v[192:195], v[74:77]
	v_mfma_f32_16x16x32_bf16 v[126:129], v[140:143], v[172:175], v[126:129]
	v_mfma_f32_16x16x32_bf16 v[122:125], v[148:151], v[172:175], v[122:125]
	v_mfma_f32_16x16x32_bf16 v[110:113], v[140:143], v[180:183], v[110:113]
	v_mfma_f32_16x16x32_bf16 v[106:109], v[148:151], v[180:183], v[106:109]
	v_mfma_f32_16x16x32_bf16 v[94:97], v[140:143], v[188:191], v[94:97]
	v_mfma_f32_16x16x32_bf16 v[90:93], v[148:151], v[188:191], v[90:93]
	v_mfma_f32_16x16x32_bf16 v[78:81], v[140:143], v[196:199], v[78:81]
	v_mfma_f32_16x16x32_bf16 v[74:77], v[148:151], v[196:199], v[74:77]
	s_setprio 0
	s_barrier
	s_add_i32 s52, 0, 0x1c000
	s_add_i32 s53, s68, s54
	v_add_u32_e32 v161, s52, v153
	v_lshl_add_u64 v[156:157], v[156:157], 0, s[94:95]
	s_mov_b32 m0, s53
	ds_read_b128 v[224:227], v161
	ds_read_b128 v[228:231], v161 offset:1024
	ds_read_b128 v[232:235], v161 offset:2048
	ds_read_b128 v[236:239], v161 offset:3072
	global_load_lds_dwordx4 v[156:157], off
	v_lshl_add_u64 v[156:157], v[200:201], 0, s[94:95]
	s_add_i32 m0, s53, 0x2000
	s_nop 0
	global_load_lds_dwordx4 v[156:157], off
	s_barrier
	s_waitcnt lgkmcnt(0)
	s_setprio 1
	s_waitcnt lgkmcnt(0)
	v_mfma_f32_16x16x32_bf16 v[118:121], v[224:227], v[168:171], v[118:121]
	v_mfma_f32_16x16x32_bf16 v[114:117], v[232:235], v[168:171], v[114:117]
	v_mfma_f32_16x16x32_bf16 v[102:105], v[224:227], v[176:179], v[102:105]
	v_mfma_f32_16x16x32_bf16 v[98:101], v[232:235], v[176:179], v[98:101]
	v_mfma_f32_16x16x32_bf16 v[86:89], v[224:227], v[184:187], v[86:89]
	v_mfma_f32_16x16x32_bf16 v[82:85], v[232:235], v[184:187], v[82:85]
	v_mfma_f32_16x16x32_bf16 v[70:73], v[224:227], v[192:195], v[70:73]
	v_mfma_f32_16x16x32_bf16 v[66:69], v[232:235], v[192:195], v[66:69]
	v_mfma_f32_16x16x32_bf16 v[118:121], v[228:231], v[172:175], v[118:121]
	v_mfma_f32_16x16x32_bf16 v[114:117], v[236:239], v[172:175], v[114:117]
	v_mfma_f32_16x16x32_bf16 v[102:105], v[228:231], v[180:183], v[102:105]
	v_mfma_f32_16x16x32_bf16 v[98:101], v[236:239], v[180:183], v[98:101]
	v_mfma_f32_16x16x32_bf16 v[86:89], v[228:231], v[188:191], v[86:89]
	v_mfma_f32_16x16x32_bf16 v[82:85], v[236:239], v[188:191], v[82:85]
	v_mfma_f32_16x16x32_bf16 v[70:73], v[228:231], v[196:199], v[70:73]
	v_mfma_f32_16x16x32_bf16 v[66:69], v[236:239], v[196:199], v[66:69]
	s_setprio 0
	s_mov_b32 m0, s59
	v_lshl_add_u64 v[156:157], v[210:211], 0, s[94:95]
	s_barrier
	ds_read_b128 v[168:171], v155 offset:49152
	ds_read_b128 v[172:175], v155 offset:50176
	ds_read_b128 v[176:179], v155 offset:51200
	ds_read_b128 v[180:183], v155 offset:52224
	ds_read_b128 v[184:187], v155 offset:53248
	ds_read_b128 v[188:191], v155 offset:54272
	ds_read_b128 v[192:195], v155 offset:55296
	ds_read_b128 v[196:199], v155 offset:56320
	global_load_lds_dwordx4 v[156:157], off
	v_lshl_add_u64 v[156:157], v[212:213], 0, s[94:95]
	s_mov_b32 m0, s60
	s_nop 0
	global_load_lds_dwordx4 v[156:157], off
	s_barrier
	s_waitcnt lgkmcnt(0)
	s_setprio 1
	s_waitcnt lgkmcnt(0)
	v_mfma_f32_16x16x32_bf16 v[62:65], v[136:139], v[168:171], v[62:65]
	v_mfma_f32_16x16x32_bf16 v[58:61], v[144:147], v[168:171], v[58:61]
	v_mfma_f32_16x16x32_bf16 v[46:49], v[136:139], v[176:179], v[46:49]
	v_mfma_f32_16x16x32_bf16 v[42:45], v[144:147], v[176:179], v[42:45]
	v_mfma_f32_16x16x32_bf16 v[30:33], v[136:139], v[184:187], v[30:33]
	v_mfma_f32_16x16x32_bf16 v[26:29], v[144:147], v[184:187], v[26:29]
	v_mfma_f32_16x16x32_bf16 v[14:17], v[136:139], v[192:195], v[14:17]
	v_mfma_f32_16x16x32_bf16 v[10:13], v[144:147], v[192:195], v[10:13]
	v_mfma_f32_16x16x32_bf16 v[62:65], v[140:143], v[172:175], v[62:65]
	v_mfma_f32_16x16x32_bf16 v[58:61], v[148:151], v[172:175], v[58:61]
	v_mfma_f32_16x16x32_bf16 v[46:49], v[140:143], v[180:183], v[46:49]
	v_mfma_f32_16x16x32_bf16 v[42:45], v[148:151], v[180:183], v[42:45]
	v_mfma_f32_16x16x32_bf16 v[30:33], v[140:143], v[188:191], v[30:33]
	v_mfma_f32_16x16x32_bf16 v[26:29], v[148:151], v[188:191], v[26:29]
	v_mfma_f32_16x16x32_bf16 v[14:17], v[140:143], v[196:199], v[14:17]
	v_mfma_f32_16x16x32_bf16 v[10:13], v[148:151], v[196:199], v[10:13]
	s_setprio 0
	s_barrier
	s_add_u32 s50, s50, 0x80080
	s_addc_u32 s51, s51, 0
	s_add_i32 s52, s52, s54
	v_lshl_add_u64 v[136:137], s[50:51], 0, v[0:1]
	s_mov_b32 m0, s52
	s_nop 0
	global_load_lds_dwordx4 v[136:137], off
	v_lshl_add_u64 v[136:137], s[50:51], 0, v[130:131]
	s_add_i32 m0, s52, 0x2000
	s_nop 0
	global_load_lds_dwordx4 v[136:137], off
	s_waitcnt vmcnt(6)
	s_barrier
	s_setprio 1
	v_mfma_f32_16x16x32_bf16 v[54:57], v[224:227], v[168:171], v[54:57]
	v_mfma_f32_16x16x32_bf16 v[50:53], v[232:235], v[168:171], v[50:53]
	v_mfma_f32_16x16x32_bf16 v[38:41], v[224:227], v[176:179], v[38:41]
	v_mfma_f32_16x16x32_bf16 v[34:37], v[232:235], v[176:179], v[34:37]
	v_mfma_f32_16x16x32_bf16 v[22:25], v[224:227], v[184:187], v[22:25]
	v_mfma_f32_16x16x32_bf16 v[18:21], v[232:235], v[184:187], v[18:21]
	v_mfma_f32_16x16x32_bf16 v[6:9], v[224:227], v[192:195], v[6:9]
	v_mfma_f32_16x16x32_bf16 v[2:5], v[232:235], v[192:195], v[2:5]
	v_mfma_f32_16x16x32_bf16 v[54:57], v[228:231], v[172:175], v[54:57]
	v_mfma_f32_16x16x32_bf16 v[50:53], v[236:239], v[172:175], v[50:53]
	v_mfma_f32_16x16x32_bf16 v[38:41], v[228:231], v[180:183], v[38:41]
	v_mfma_f32_16x16x32_bf16 v[34:37], v[236:239], v[180:183], v[34:37]
	v_mfma_f32_16x16x32_bf16 v[22:25], v[228:231], v[188:191], v[22:25]
	v_mfma_f32_16x16x32_bf16 v[18:21], v[236:239], v[188:191], v[18:21]
	v_mfma_f32_16x16x32_bf16 v[6:9], v[228:231], v[196:199], v[6:9]
	v_mfma_f32_16x16x32_bf16 v[2:5], v[236:239], v[196:199], v[2:5]
	s_setprio 0
	s_add_u32 s0, s0, 0x100
	s_addc_u32 s1, s1, 0
	s_add_u32 s13, s13, 0x100
	s_addc_u32 s66, s66, 0
	s_cmp_ge_i32 s67, s41
	s_mov_b32 s50, s67
	s_barrier
	s_cbranch_scc0 .LBB0_282
	s_cmp_eq_u32 s63, 2
	s_cbranch_scc1 .Lepi6_orig
	v_readlane_b32 s90, v255, 17
	v_readlane_b32 s91, v255, 18
	v_readlane_b32 s96, v255, 19
	v_readlane_b32 s97, v255, 20
	v_readlane_b32 s8, v255, 25
	v_readlane_b32 s9, v255, 26
	v_readlane_b32 s68, v253, 58
	v_readlane_b32 s69, v253, 59
	v_lshl_or_b32 v156, s64, 8, v154
	v_lshlrev_b32_e32 v156, 2, v156
	v_lshl_add_u32 v157, v152, 13, v156
	s_lshl_b32 s72, s65, 21
	s_add_u32 s74, s68, s72
	s_addc_u32 s75, s69, 0
	s_add_u32 s76, s22, s72
	s_addc_u32 s77, s23, 0
	s_lshr_b32 s73, s65, 3
	s_mul_i32 s73, s73, 0xc000
	s_add_u32 s73, s73, 0x4000
	s_add_u32 s70, s90, s73
	s_addc_u32 s71, s91, 0
	global_load_dwordx4 v[140:143], v156, s[70:71]
	global_load_dwordx4 v[144:147], v156, s[70:71] offset:64
	global_load_dwordx4 v[148:151], v156, s[70:71] offset:512
	global_load_dwordx4 v[168:171], v156, s[70:71] offset:576
	global_load_dwordx4 v[224:227], v157, s[74:75] nt
	global_load_dwordx4 v[228:231], v157, s[74:75] offset:64 nt
	global_load_dwordx4 v[232:235], v157, s[74:75] offset:512 nt
	global_load_dwordx4 v[236:239], v157, s[74:75] offset:576 nt
	s_add_u32 s74, s74, 0x20000
	s_addc_u32 s75, s75, 0
	global_load_dwordx4 v[240:243], v157, s[74:75] nt
	global_load_dwordx4 v[244:247], v157, s[74:75] offset:64 nt
	s_waitcnt vmcnt(5)
	v_pk_fma_f32 v[128:129], v[128:129], v[142:143], v[226:227]
	v_pk_fma_f32 v[126:127], v[126:127], v[140:141], v[224:225]
	global_store_dwordx4 v157, v[126:129], s[76:77]
	global_load_dwordx4 v[224:227], v157, s[74:75] offset:512 nt
	s_waitcnt vmcnt(6)
	v_pk_fma_f32 v[124:125], v[124:125], v[146:147], v[230:231]
	v_pk_fma_f32 v[122:123], v[122:123], v[144:145], v[228:229]
	global_store_dwordx4 v157, v[122:125], s[76:77] offset:64
	global_load_dwordx4 v[228:231], v157, s[74:75] offset:576 nt
	s_waitcnt vmcnt(7)
	v_pk_fma_f32 v[120:121], v[120:121], v[150:151], v[234:235]
	v_pk_fma_f32 v[118:119], v[118:119], v[148:149], v[232:233]
	global_store_dwordx4 v157, v[118:121], s[76:77] offset:512
	s_add_u32 s74, s74, 0x20000
	s_addc_u32 s75, s75, 0
	global_load_dwordx4 v[232:235], v157, s[74:75] nt
	s_waitcnt vmcnt(8)
	v_pk_fma_f32 v[116:117], v[116:117], v[170:171], v[238:239]
	v_pk_fma_f32 v[114:115], v[114:115], v[168:169], v[236:237]
	global_store_dwordx4 v157, v[114:117], s[76:77] offset:576
	global_load_dwordx4 v[236:239], v157, s[74:75] offset:64 nt
	s_add_u32 s76, s76, 0x20000
	s_addc_u32 s77, s77, 0
	s_waitcnt vmcnt(9)
	v_pk_fma_f32 v[112:113], v[112:113], v[142:143], v[242:243]
	v_pk_fma_f32 v[110:111], v[110:111], v[140:141], v[240:241]
	global_store_dwordx4 v157, v[110:113], s[76:77]
	global_load_dwordx4 v[240:243], v157, s[74:75] offset:512 nt
	s_waitcnt vmcnt(10)
	v_pk_fma_f32 v[108:109], v[108:109], v[146:147], v[246:247]
	v_pk_fma_f32 v[106:107], v[106:107], v[144:145], v[244:245]
	global_store_dwordx4 v157, v[106:109], s[76:77] offset:64
	global_load_dwordx4 v[244:247], v157, s[74:75] offset:576 nt
	s_waitcnt vmcnt(10)
	v_pk_fma_f32 v[104:105], v[104:105], v[150:151], v[226:227]
	v_pk_fma_f32 v[102:103], v[102:103], v[148:149], v[224:225]
	global_store_dwordx4 v157, v[102:105], s[76:77] offset:512
	s_add_u32 s74, s74, 0x20000
	s_addc_u32 s75, s75, 0
	global_load_dwordx4 v[224:227], v157, s[74:75] nt
	s_waitcnt vmcnt(10)
	v_pk_fma_f32 v[100:101], v[100:101], v[170:171], v[230:231]
	v_pk_fma_f32 v[98:99], v[98:99], v[168:169], v[228:229]
	global_store_dwordx4 v157, v[98:101], s[76:77] offset:576
	global_load_dwordx4 v[228:231], v157, s[74:75] offset:64 nt
	s_add_u32 s76, s76, 0x20000
	s_addc_u32 s77, s77, 0
	s_waitcnt vmcnt(10)
	v_pk_fma_f32 v[96:97], v[96:97], v[142:143], v[234:235]
	v_pk_fma_f32 v[94:95], v[94:95], v[140:141], v[232:233]
	global_store_dwordx4 v157, v[94:97], s[76:77]
	global_load_dwordx4 v[232:235], v157, s[74:75] offset:512 nt
	s_waitcnt vmcnt(10)
	v_pk_fma_f32 v[92:93], v[92:93], v[146:147], v[238:239]
	v_pk_fma_f32 v[90:91], v[90:91], v[144:145], v[236:237]
	global_store_dwordx4 v157, v[90:93], s[76:77] offset:64
	global_load_dwordx4 v[236:239], v157, s[74:75] offset:576 nt
	s_waitcnt vmcnt(10)
	v_pk_fma_f32 v[88:89], v[88:89], v[150:151], v[242:243]
	v_pk_fma_f32 v[86:87], v[86:87], v[148:149], v[240:241]
	global_store_dwordx4 v157, v[86:89], s[76:77] offset:512
	s_add_u32 s74, s74, 0xa0000
	s_addc_u32 s75, s75, 0
	global_load_dwordx4 v[240:243], v157, s[74:75] nt
	s_waitcnt vmcnt(10)
	v_pk_fma_f32 v[84:85], v[84:85], v[170:171], v[246:247]
	v_pk_fma_f32 v[82:83], v[82:83], v[168:169], v[244:245]
	global_store_dwordx4 v157, v[82:85], s[76:77] offset:576
	global_load_dwordx4 v[244:247], v157, s[74:75] offset:64 nt
	s_add_u32 s76, s76, 0x20000
	s_addc_u32 s77, s77, 0
	s_waitcnt vmcnt(10)
	v_pk_fma_f32 v[80:81], v[80:81], v[142:143], v[226:227]
	v_pk_fma_f32 v[78:79], v[78:79], v[140:141], v[224:225]
	global_store_dwordx4 v157, v[78:81], s[76:77]
	global_load_dwordx4 v[224:227], v157, s[74:75] offset:512 nt
	s_waitcnt vmcnt(10)
	v_pk_fma_f32 v[76:77], v[76:77], v[146:147], v[230:231]
	v_pk_fma_f32 v[74:75], v[74:75], v[144:145], v[228:229]
	global_store_dwordx4 v157, v[74:77], s[76:77] offset:64
	global_load_dwordx4 v[228:231], v157, s[74:75] offset:576 nt
	s_waitcnt vmcnt(10)
	v_pk_fma_f32 v[72:73], v[72:73], v[150:151], v[234:235]
	v_pk_fma_f32 v[70:71], v[70:71], v[148:149], v[232:233]
	global_store_dwordx4 v157, v[70:73], s[76:77] offset:512
	s_add_u32 s74, s74, 0x20000
	s_addc_u32 s75, s75, 0
	global_load_dwordx4 v[232:235], v157, s[74:75] nt
	s_waitcnt vmcnt(10)
	v_pk_fma_f32 v[68:69], v[68:69], v[170:171], v[238:239]
	v_pk_fma_f32 v[66:67], v[66:67], v[168:169], v[236:237]
	global_store_dwordx4 v157, v[66:69], s[76:77] offset:576
	global_load_dwordx4 v[236:239], v157, s[74:75] offset:64 nt
	s_add_u32 s76, s76, 0xa0000
	s_addc_u32 s77, s77, 0
	s_waitcnt vmcnt(10)
	v_pk_fma_f32 v[64:65], v[64:65], v[142:143], v[242:243]
	v_pk_fma_f32 v[62:63], v[62:63], v[140:141], v[240:241]
	global_store_dwordx4 v157, v[62:65], s[76:77]
	global_load_dwordx4 v[240:243], v157, s[74:75] offset:512 nt
	s_waitcnt vmcnt(10)
	v_pk_fma_f32 v[60:61], v[60:61], v[146:147], v[246:247]
	v_pk_fma_f32 v[58:59], v[58:59], v[144:145], v[244:245]
	global_store_dwordx4 v157, v[58:61], s[76:77] offset:64
	global_load_dwordx4 v[244:247], v157, s[74:75] offset:576 nt
	s_waitcnt vmcnt(10)
	v_pk_fma_f32 v[56:57], v[56:57], v[150:151], v[226:227]
	v_pk_fma_f32 v[54:55], v[54:55], v[148:149], v[224:225]
	global_store_dwordx4 v157, v[54:57], s[76:77] offset:512
	s_add_u32 s74, s74, 0x20000
	s_addc_u32 s75, s75, 0
	global_load_dwordx4 v[224:227], v157, s[74:75] nt
	s_waitcnt vmcnt(10)
	v_pk_fma_f32 v[52:53], v[52:53], v[170:171], v[230:231]
	v_pk_fma_f32 v[50:51], v[50:51], v[168:169], v[228:229]
	global_store_dwordx4 v157, v[50:53], s[76:77] offset:576
	global_load_dwordx4 v[228:231], v157, s[74:75] offset:64 nt
	s_add_u32 s76, s76, 0x20000
	s_addc_u32 s77, s77, 0
	s_waitcnt vmcnt(10)
	v_pk_fma_f32 v[48:49], v[48:49], v[142:143], v[234:235]
	v_pk_fma_f32 v[46:47], v[46:47], v[140:141], v[232:233]
	global_store_dwordx4 v157, v[46:49], s[76:77]
	global_load_dwordx4 v[232:235], v157, s[74:75] offset:512 nt
	s_waitcnt vmcnt(10)
	v_pk_fma_f32 v[44:45], v[44:45], v[146:147], v[238:239]
	v_pk_fma_f32 v[42:43], v[42:43], v[144:145], v[236:237]
	global_store_dwordx4 v157, v[42:45], s[76:77] offset:64
	global_load_dwordx4 v[236:239], v157, s[74:75] offset:576 nt
	s_waitcnt vmcnt(10)
	v_pk_fma_f32 v[40:41], v[40:41], v[150:151], v[242:243]
	v_pk_fma_f32 v[38:39], v[38:39], v[148:149], v[240:241]
	global_store_dwordx4 v157, v[38:41], s[76:77] offset:512
	s_add_u32 s74, s74, 0x20000
	s_addc_u32 s75, s75, 0
	global_load_dwordx4 v[240:243], v157, s[74:75] nt
	s_waitcnt vmcnt(10)
	v_pk_fma_f32 v[36:37], v[36:37], v[170:171], v[246:247]
	v_pk_fma_f32 v[34:35], v[34:35], v[168:169], v[244:245]
	global_store_dwordx4 v157, v[34:37], s[76:77] offset:576
	global_load_dwordx4 v[244:247], v157, s[74:75] offset:64 nt
	s_add_u32 s76, s76, 0x20000
	s_addc_u32 s77, s77, 0
	s_waitcnt vmcnt(10)
	v_pk_fma_f32 v[32:33], v[32:33], v[142:143], v[226:227]
	v_pk_fma_f32 v[30:31], v[30:31], v[140:141], v[224:225]
	global_store_dwordx4 v157, v[30:33], s[76:77]
	global_load_dwordx4 v[224:227], v157, s[74:75] offset:512 nt
	s_waitcnt vmcnt(10)
	v_pk_fma_f32 v[28:29], v[28:29], v[146:147], v[230:231]
	v_pk_fma_f32 v[26:27], v[26:27], v[144:145], v[228:229]
	global_store_dwordx4 v157, v[26:29], s[76:77] offset:64
	global_load_dwordx4 v[228:231], v157, s[74:75] offset:576 nt
	s_waitcnt vmcnt(10)
	v_pk_fma_f32 v[24:25], v[24:25], v[150:151], v[234:235]
	v_pk_fma_f32 v[22:23], v[22:23], v[148:149], v[232:233]
	global_store_dwordx4 v157, v[22:25], s[76:77] offset:512
	s_waitcnt vmcnt(9)
	v_pk_fma_f32 v[20:21], v[20:21], v[170:171], v[238:239]
	v_pk_fma_f32 v[18:19], v[18:19], v[168:169], v[236:237]
	global_store_dwordx4 v157, v[18:21], s[76:77] offset:576
	s_add_u32 s76, s76, 0x20000
	s_addc_u32 s77, s77, 0
	s_waitcnt vmcnt(8)
	v_pk_fma_f32 v[16:17], v[16:17], v[142:143], v[242:243]
	v_pk_fma_f32 v[14:15], v[14:15], v[140:141], v[240:241]
	global_store_dwordx4 v157, v[14:17], s[76:77]
	s_waitcnt vmcnt(7)
	v_pk_fma_f32 v[12:13], v[12:13], v[146:147], v[246:247]
	v_pk_fma_f32 v[10:11], v[10:11], v[144:145], v[244:245]
	global_store_dwordx4 v157, v[10:13], s[76:77] offset:64
	s_waitcnt vmcnt(6)
	v_pk_fma_f32 v[8:9], v[8:9], v[150:151], v[226:227]
	v_pk_fma_f32 v[6:7], v[6:7], v[148:149], v[224:225]
	global_store_dwordx4 v157, v[6:9], s[76:77] offset:512
	s_waitcnt vmcnt(5)
	v_pk_fma_f32 v[4:5], v[4:5], v[170:171], v[230:231]
	v_pk_fma_f32 v[2:3], v[2:3], v[168:169], v[228:229]
	global_store_dwordx4 v157, v[2:5], s[76:77] offset:576
	s_branch .LBB0_269
.Lepi6_orig:
	v_lshl_or_b32 v136, s64, 8, v154
	v_lshl_add_u32 v140, s65, 8, v152
	v_ashrrev_i32_e32 v137, 31, v136
	s_movk_i32 s0, 0x2080
	v_ashrrev_i32_e32 v156, 11, v140
	v_cmp_gt_i32_e32 vcc, s0, v140
	v_lshlrev_b64 v[138:139], 2, v[136:137]
	v_ashrrev_i32_e32 v141, 31, v140
	s_and_saveexec_b64 s[50:51], vcc
	v_readlane_b32 s90, v255, 17
	v_readlane_b32 s96, v255, 19
	v_readlane_b32 s8, v255, 25
	v_readlane_b32 s91, v255, 18
	v_readlane_b32 s97, v255, 20
	v_readlane_b32 s9, v255, 26
	s_cbranch_execz .LBB0_301
	v_add_u32_e32 v148, 0xffffe000, v140
	v_lshrrev_b32_e32 v142, 4, v148
	s_movk_i32 s0, 0x2000
	v_add_u32_e32 v142, 4, v142
	v_cmp_gt_i32_e32 vcc, s0, v140
	s_mov_b32 s0, 0xc000
	v_readlane_b32 s64, v253, 58
	v_cndmask_b32_e32 v144, v142, v156, vcc
	v_mov_b64_e32 v[142:143], s[90:91]
	v_mad_i64_i32 v[142:143], s[0:1], v144, s0, v[142:143]
	v_mov_b32_e32 v149, v1
	v_lshl_add_u64 v[142:143], v[142:143], 0, v[138:139]
	s_mov_b64 s[0:1], 0x4000
	v_lshlrev_b64 v[146:147], 13, v[140:141]
	v_readlane_b32 s65, v253, 59
	v_readlane_b32 s66, v253, 60
	v_readlane_b32 s67, v253, 61
	v_lshlrev_b64 v[150:151], 13, v[148:149]
	v_lshl_add_u64 v[144:145], v[142:143], 0, s[0:1]
	v_lshl_add_u64 v[142:143], s[22:23], 0, v[146:147]
	v_lshl_add_u64 v[146:147], s[64:65], 0, v[146:147]
	v_lshl_add_u64 v[150:151], s[66:67], 0, v[150:151]
	s_cmp_lg_u32 s63, 2
	v_cndmask_b32_e32 v147, v151, v147, vcc
	v_cndmask_b32_e32 v146, v150, v146, vcc
	s_cselect_b64 s[52:53], -1, 0
	v_lshl_add_u64 v[146:147], v[146:147], 0, v[138:139]
	s_mov_b64 s[0:1], -1
	s_and_b64 vcc, exec, s[52:53]
	v_readlane_b32 s68, v253, 62
	v_readlane_b32 s69, v253, 63
	v_readlane_b32 s70, v254, 0
	v_readlane_b32 s71, v254, 1
	v_readlane_b32 s72, v254, 2
	v_readlane_b32 s73, v254, 3
	v_readlane_b32 s74, v254, 4
	v_readlane_b32 s75, v254, 5
	v_readlane_b32 s76, v254, 6
	v_readlane_b32 s77, v254, 7
	v_readlane_b32 s78, v254, 8
	v_readlane_b32 s79, v254, 9
	s_cbranch_vccz .LBB0_286
	global_load_dwordx4 v[168:171], v[146:147], off nt
	global_load_dwordx4 v[172:175], v[144:145], off
	v_lshl_add_u64 v[150:151], v[136:137], 2, v[142:143]
	s_mov_b64 s[0:1], 0
	s_waitcnt vmcnt(0)
	v_pk_fma_f32 v[170:171], v[128:129], v[174:175], v[170:171]
	v_pk_fma_f32 v[168:169], v[126:127], v[172:173], v[168:169]
	global_store_dwordx4 v[150:151], v[168:171], off
